# barrier-word zeroing at kernel start moved from workgroup 0 to the last workgroup (one weight tile less in P0)
# baseline (speedup 1.0000x reference)
; #define LAS __attribute__((address_space(3)))
; __device__ __forceinline__ CArgsP get_args() { CArgsP p = (CArgsP)__builtin_amdgcn_kernarg_segment_ptr(); asm volatile("" : "+s"(p)); return p; }
; __global__ void __launch_bounds__(512, 2) mega_fwd(Args a_unused) {
;     ...
;     if (tid < 64) ((LAS unsigned*)(lds + 131072))[tid] = 0u;
;     __syncthreads();
;     { CArgsP a = get_args(); phase0(a, lds, wave, lane);
;       if (bx == 0) { unsigned* bw = (unsigned*)(a->ws + WS_BAR); for (int i = tid; i < (int)(BAR_BYTES / 4); i += 512) bw[i] = 0u; } }
_Z8mega_fwd4Args:
	s_load_dwordx2 s[60:61], s[0:1], 0x100
	s_load_dword s78, s[0:1], 0x108
	s_mov_b64 s[92:93], s[0:1]
	v_and_b32_e32 v164, 0x3ff, v0
	s_add_u32 s10, s92, 0x100
	v_cmp_lt_u32_e64 s[0:1], 63, v164
	s_addc_u32 s11, s93, 0
	v_readfirstlane_b32 s44, v164
	v_writelane_b32 v250, s0, 0
	v_cmp_gt_u32_e64 s[8:9], 64, v164
	v_lshl_add_u32 v149, v164, 2, 0
	v_writelane_b32 v250, s1, 1
	s_and_saveexec_b64 s[4:5], s[8:9]
	v_lshl_add_u32 v1, v164, 2, 0
	v_add_u32_e32 v1, 0x20000, v1
	v_mov_b32_e32 v2, 0
	ds_write_b32 v1, v2
	s_or_b64 exec, exec, s[4:5]
	s_mov_b64 s[18:19], s[92:93]
	s_waitcnt lgkmcnt(0)
	s_barrier
	s_add_i32 s16, s60, -1
	s_cmp_lg_u32 s2, s16
	s_cbranch_scc1 .Lz_done
	s_load_dwordx2 s[16:17], s[92:93], 0xf8
	v_lshlrev_b32_e32 v1, 2, v164
	v_mov_b32_e32 v2, 0
	s_waitcnt lgkmcnt(0)
	s_add_u32 s16, s16, 0x80000
	s_addc_u32 s17, s17, 0
	global_store_dword v1, v2, s[16:17]
	global_store_dword v1, v2, s[16:17] offset:2048
	v_add_u32_e32 v1, 0x1000, v1
	global_store_dword v1, v2, s[16:17]
	global_store_dword v1, v2, s[16:17] offset:2048
	v_add_u32_e32 v1, 0x1000, v1
	global_store_dword v1, v2, s[16:17]
	global_store_dword v1, v2, s[16:17] offset:2048
	v_add_u32_e32 v1, 0x1000, v1
	global_store_dword v1, v2, s[16:17]
	global_store_dword v1, v2, s[16:17] offset:2048
	s_waitcnt vmcnt(0)
	s_barrier
	s_cmp_lg_u32 s44, 0
	s_cbranch_scc1 .Lz_done
	buffer_wbl2 sc1
	s_waitcnt vmcnt(0)
	v_mov_b32_e32 v1, 0x3e80
	v_mov_b32_e32 v2, 0x5a17c0de
	global_store_dword v1, v2, s[16:17] sc0 sc1
	s_waitcnt vmcnt(0)
	buffer_inv sc1
	s_waitcnt vmcnt(0)

; #define LAS __attribute__((address_space(3)))
; __device__ __forceinline__ CArgsP get_args() { CArgsP p = (CArgsP)__builtin_amdgcn_kernarg_segment_ptr(); asm volatile("" : "+s"(p)); return p; }
; #define PH(k) for (int r_ = 0, n_ = probe_reps(k); r_ < n_; ++r_)
; __global__ void __launch_bounds__(512, 2) mega_fwd(Args a_unused) {
;     ...
;       if (bx == 0) { unsigned* bw = (unsigned*)(a->ws + WS_BAR); for (int i = tid; i < (int)(BAR_BYTES / 4); i += 512) bw[i] = 0u; } }
;     grid.sync();
;     { CArgsP a = get_args(); (void)xcd_barrier_post((unsigned*)(a->ws + WS_BAR), (volatile LAS unsigned*)(lds + LDS_MISC)); }
;     PH(1) { CArgsP a = get_args(); unsigned char* ws = a->ws; unsigned* cnt = (unsigned*)(ws + WS_BAR) + CNT_FFN1;
.Lcg_277:
	s_or_b64 exec, exec, s[4:5]
	s_add_i32 s6, s60, -1
	s_cmp_lg_u32 s2, s6
	s_cbranch_scc1 .Lcg_noreset
	s_cmp_lg_u32 s44, 0
	s_cbranch_scc1 .Lcg_noreset
	s_load_dwordx2 s[6:7], s[92:93], 0xf8
	v_mov_b32_e32 v0, 0x83e80
	v_mov_b32_e32 v1, 0
	s_waitcnt lgkmcnt(0)
	global_store_dword v0, v1, s[6:7] sc0 sc1
